# EpiResid: second row-half base loads (m=0..2) issued with the first half's loads; store-throttling waits removed
# baseline (speedup 1.0000x reference)
; __device__ __forceinline__ unsigned cvt_pk_bf16(float lo, float hi) { bf16v2_t r = __builtin_convertvector((f32x2_t){lo, hi}, bf16v2_t); return __builtin_bit_cast(unsigned, r); }
;     static __device__ __forceinline__ f32x4 unpack4(u32x2_ t) { return (f32x4){__uint_as_float(t.x << 16), __uint_as_float(t.x & 0xffff0000u), __uint_as_float(t.y << 16), __uint_as_float(t.y & 0xffff0000u)}; }
;     __device__ __forceinline__ void operator()(const f32x4 (&acc)[2][2][4][2], const Unit& u, int wr, int wc, int fr, int fq) const {
;     ...
;             for (int ai = 0; ai < 2; ++ai) {
;                 u32x2_ bb[4][2][2];
; #pragma unroll
;                 for (int m = 0; m < 4; ++m)
; #pragma unroll
;                     for (int bj = 0; bj < 2; ++bj)
; #pragma unroll
;                         for (int n = 0; n < 2; ++n) bb[m][bj][n] = *(const u32x2_*)(xb + (size_t)(row0 + ai * HALF + m * 16) * ldc + col0 + bj * HALF + n * 16);
; #pragma unroll
;                 for (int m = 0; m < 4; ++m) {
;                     const int row = row0 + ai * HALF + m * 16; const size_t off = (size_t)row * ldc + col0; float ss = 0.f;
; #pragma unroll
;                     for (int bj = 0; bj < 2; ++bj)
; #pragma unroll
;                         for (int n = 0; n < 2; ++n) { const size_t o = off + bj * HALF + n * 16;
;                             f32x4 v = unpack4(bb[m][bj][n]) + acc[ai][bj][m][n] * scale;
;                             u32x2_ w; w.x = cvt_pk_bf16(v[0], v[1]); w.y = cvt_pk_bf16(v[2], v[3]); *(u32x2_*)(xb + o) = w;
;                             if (out32) *(f32x4*)(out32 + o) = v; else v = unpack4(w);
;                             ss += (v[0] * v[0] + v[1] * v[1]) + (v[2] * v[2] + v[3] * v[3]); }
;                     ss += __shfl_xor(ss, 16); ss += __shfl_xor(ss, 32);
;                     if (fq == 0) ssq[(size_t)row * 16 + 4 * u.pn + wc] = ss;
.LBB0_224:
	s_mov_b64 s[14:15], 0x40000
	v_lshlrev_b64 v[214:215], 1, v[144:145]
	v_lshl_add_u64 v[148:149], s[26:27], 0, v[214:215]
	v_lshlrev_b64 v[216:217], 11, v[146:147]
	s_waitcnt lgkmcnt(0)
	v_lshl_add_u64 v[150:151], v[148:149], 0, v[216:217]
	global_load_dwordx2 v[218:219], v[150:151], off
	global_load_dwordx2 v[198:199], v[150:151], off offset:32
	global_load_dwordx2 v[196:197], v[150:151], off offset:256
	global_load_dwordx2 v[194:195], v[150:151], off offset:288
	v_lshl_add_u64 v[246:247], v[150:151], 0, s[14:15]
	global_load_dwordx2 v[222:223], v[246:247], off
	global_load_dwordx2 v[224:225], v[246:247], off offset:32
	global_load_dwordx2 v[226:227], v[246:247], off offset:256
	global_load_dwordx2 v[228:229], v[246:247], off offset:288
	v_or_b32_e32 v182, 16, v146
	v_ashrrev_i32_e32 v183, 31, v182
	v_lshlrev_b64 v[150:151], 11, v[182:183]
	v_or_b32_e32 v158, 32, v146
	v_lshl_add_u64 v[150:151], v[148:149], 0, v[150:151]
	v_ashrrev_i32_e32 v159, 31, v158
	global_load_dwordx2 v[192:193], v[150:151], off
	global_load_dwordx2 v[190:191], v[150:151], off offset:32
	global_load_dwordx2 v[188:189], v[150:151], off offset:256
	global_load_dwordx2 v[186:187], v[150:151], off offset:288
	v_lshl_add_u64 v[246:247], v[150:151], 0, s[14:15]
	global_load_dwordx2 v[230:231], v[246:247], off
	global_load_dwordx2 v[232:233], v[246:247], off offset:32
	global_load_dwordx2 v[234:235], v[246:247], off offset:256
	global_load_dwordx2 v[236:237], v[246:247], off offset:288
	v_lshlrev_b64 v[150:151], 11, v[158:159]
	v_lshl_add_u64 v[150:151], v[148:149], 0, v[150:151]
	global_load_dwordx2 v[184:185], v[150:151], off
	global_load_dwordx2 v[180:181], v[150:151], off offset:32
	global_load_dwordx2 v[178:179], v[150:151], off offset:256
	global_load_dwordx2 v[162:163], v[150:151], off offset:288
	v_lshl_add_u64 v[246:247], v[150:151], 0, s[14:15]
	global_load_dwordx2 v[238:239], v[246:247], off
	global_load_dwordx2 v[240:241], v[246:247], off offset:32
	global_load_dwordx2 v[242:243], v[246:247], off offset:256
	global_load_dwordx2 v[244:245], v[246:247], off offset:288
	v_or_b32_e32 v150, 48, v146
	v_ashrrev_i32_e32 v151, 31, v150
	v_lshlrev_b64 v[152:153], 11, v[150:151]
	v_lshl_add_u64 v[152:153], v[148:149], 0, v[152:153]
	global_load_dwordx2 v[160:161], v[152:153], off
	global_load_dwordx2 v[156:157], v[152:153], off offset:32
	global_load_dwordx2 v[154:155], v[152:153], off offset:256
	s_nop 0
	global_load_dwordx2 v[152:153], v[152:153], off offset:288
	v_mov_b32_e32 v137, v136
	s_waitcnt vmcnt(0)
	v_lshlrev_b32_e32 v220, 16, v218
	v_and_b32_e32 v221, 0xffff0000, v218
	v_lshlrev_b32_e32 v218, 16, v219
	v_and_b32_e32 v219, 0xffff0000, v219
	v_pk_fma_f32 v[132:133], v[138:139], v[132:133], v[220:221]
	v_pk_fma_f32 v[134:135], v[136:137], v[134:135], v[218:219]
	v_cvt_pk_bf16_f32 v218, v132, v133
	v_cvt_pk_bf16_f32 v219, v134, v135
	v_lshl_add_u64 v[132:133], s[26:27], 0, v[216:217]
	v_and_b32_e32 v135, 0xffff0000, v218
	v_lshl_add_u64 v[132:133], v[132:133], 0, v[214:215]
	v_lshlrev_b32_e32 v134, 16, v218
	v_and_b32_e32 v214, 0xffff0000, v219
	v_mul_f32_e32 v135, v135, v135
	v_lshlrev_b32_e32 v213, 16, v219
	v_fmac_f32_e32 v135, v134, v134
	v_mul_f32_e32 v134, v214, v214
	v_fmac_f32_e32 v134, v213, v213
	v_add_f32_e32 v213, v135, v134
	v_lshlrev_b32_e32 v134, 16, v198
	v_and_b32_e32 v135, 0xffff0000, v198
	v_lshlrev_b32_e32 v198, 16, v199
	v_and_b32_e32 v199, 0xffff0000, v199
	v_pk_fma_f32 v[130:131], v[136:137], v[130:131], v[198:199]
	v_pk_fma_f32 v[128:129], v[138:139], v[128:129], v[134:135]
	global_store_dwordx2 v[132:133], v[218:219], off
	v_cvt_pk_bf16_f32 v128, v128, v129
	v_cvt_pk_bf16_f32 v129, v130, v131
	global_store_dwordx2 v[132:133], v[128:129], off offset:32
	v_lshlrev_b32_e32 v130, 16, v128
	v_and_b32_e32 v128, 0xffff0000, v128
	v_lshlrev_b32_e32 v131, 16, v129
	v_and_b32_e32 v129, 0xffff0000, v129
	v_mul_f32_e32 v128, v128, v128
	v_mul_f32_e32 v129, v129, v129
	v_fmac_f32_e32 v128, v130, v130
	v_fmac_f32_e32 v129, v131, v131
	v_add_f32_e32 v128, v128, v129
	v_add_f32_e32 v134, v213, v128
	v_lshlrev_b32_e32 v128, 16, v196
	v_and_b32_e32 v129, 0xffff0000, v196
	v_lshlrev_b32_e32 v130, 16, v197
	v_and_b32_e32 v131, 0xffff0000, v197
	v_pk_fma_f32 v[126:127], v[136:137], v[126:127], v[130:131]
	v_pk_fma_f32 v[124:125], v[138:139], v[124:125], v[128:129]
	s_nop 0
	v_cvt_pk_bf16_f32 v124, v124, v125
	v_cvt_pk_bf16_f32 v125, v126, v127
	global_store_dwordx2 v[132:133], v[124:125], off offset:256
	v_lshlrev_b32_e32 v126, 16, v124
	v_and_b32_e32 v124, 0xffff0000, v124
	v_lshlrev_b32_e32 v127, 16, v125
	v_and_b32_e32 v125, 0xffff0000, v125
	v_mul_f32_e32 v124, v124, v124
	v_mul_f32_e32 v125, v125, v125
	v_fmac_f32_e32 v124, v126, v126
	v_fmac_f32_e32 v125, v127, v127
	v_add_f32_e32 v124, v124, v125
	v_add_f32_e32 v128, v134, v124
	v_lshlrev_b32_e32 v124, 16, v194
	v_and_b32_e32 v125, 0xffff0000, v194
	v_lshlrev_b32_e32 v126, 16, v195
	v_and_b32_e32 v127, 0xffff0000, v195
	v_pk_fma_f32 v[122:123], v[136:137], v[122:123], v[126:127]
	v_pk_fma_f32 v[120:121], v[138:139], v[120:121], v[124:125]
	s_nop 0
	v_cvt_pk_bf16_f32 v120, v120, v121
	v_cvt_pk_bf16_f32 v121, v122, v123
	global_store_dwordx2 v[132:133], v[120:121], off offset:288
	v_lshlrev_b32_e32 v122, 16, v120
	v_and_b32_e32 v120, 0xffff0000, v120
	v_lshlrev_b32_e32 v123, 16, v121
	v_and_b32_e32 v121, 0xffff0000, v121
	v_mul_f32_e32 v120, v120, v120
	v_mul_f32_e32 v121, v121, v121
	v_fmac_f32_e32 v120, v122, v122
	v_fmac_f32_e32 v121, v123, v123
	v_add_f32_e32 v120, v120, v121
	v_add_f32_e32 v120, v128, v120
	ds_bpermute_b32 v121, v212, v120
	s_waitcnt lgkmcnt(0)
	v_add_f32_e32 v120, v120, v121
	ds_bpermute_b32 v121, v211, v120
	s_and_saveexec_b64 s[14:15], s[42:43]
	s_cbranch_execz .LBB0_226
	v_readlane_b32 s16, v252, 28
	v_lshlrev_b64 v[122:123], 6, v[146:147]
	v_readlane_b32 s17, v252, 29
	s_lshl_b32 s36, s58, 2
	s_waitcnt lgkmcnt(0)
	v_add_f32_e32 v120, v120, v121
	v_lshl_add_u64 v[122:123], s[16:17], 0, v[122:123]
	v_lshl_add_u64 v[122:123], s[24:25], 2, v[122:123]
	v_lshl_add_u64 v[122:123], v[122:123], 0, s[36:37]
	global_store_dword v[122:123], v120, off

; __device__ __forceinline__ unsigned cvt_pk_bf16(float lo, float hi) { bf16v2_t r = __builtin_convertvector((f32x2_t){lo, hi}, bf16v2_t); return __builtin_bit_cast(unsigned, r); }
;     static __device__ __forceinline__ f32x4 unpack4(u32x2_ t) { return (f32x4){__uint_as_float(t.x << 16), __uint_as_float(t.x & 0xffff0000u), __uint_as_float(t.y << 16), __uint_as_float(t.y & 0xffff0000u)}; }
;     __device__ __forceinline__ void operator()(const f32x4 (&acc)[2][2][4][2], const Unit& u, int wr, int wc, int fr, int fq) const {
;     ...
;                         for (int n = 0; n < 2; ++n) bb[m][bj][n] = *(const u32x2_*)(xb + (size_t)(row0 + ai * HALF + m * 16) * ldc + col0 + bj * HALF + n * 16);
; #pragma unroll
;                 for (int m = 0; m < 4; ++m) {
;                     const int row = row0 + ai * HALF + m * 16; const size_t off = (size_t)row * ldc + col0; float ss = 0.f;
; #pragma unroll
;                     for (int bj = 0; bj < 2; ++bj)
; #pragma unroll
;                         for (int n = 0; n < 2; ++n) { const size_t o = off + bj * HALF + n * 16;
;                             f32x4 v = unpack4(bb[m][bj][n]) + acc[ai][bj][m][n] * scale;
;                             u32x2_ w; w.x = cvt_pk_bf16(v[0], v[1]); w.y = cvt_pk_bf16(v[2], v[3]); *(u32x2_*)(xb + o) = w;
;                             if (out32) *(f32x4*)(out32 + o) = v; else v = unpack4(w);
;                             ss += (v[0] * v[0] + v[1] * v[1]) + (v[2] * v[2] + v[3] * v[3]); }
;                     ss += __shfl_xor(ss, 16); ss += __shfl_xor(ss, 32);
;                     if (fq == 0) ssq[(size_t)row * 16 + 4 * u.pn + wc] = ss;
.LBB0_232:
	s_or_b64 exec, exec, s[14:15]
	v_add_u32_e32 v102, 0x80, v146
	v_ashrrev_i32_e32 v103, 31, v102
	v_lshlrev_b64 v[110:111], 11, v[102:103]
	s_waitcnt lgkmcnt(0)
	v_lshl_add_u64 v[72:73], v[148:149], 0, v[110:111]
	v_mov_b32_e32 v112, v222
	v_mov_b32_e32 v113, v223
	v_mov_b32_e32 v108, v224
	v_mov_b32_e32 v109, v225
	v_mov_b32_e32 v106, v226
	v_mov_b32_e32 v107, v227
	v_mov_b32_e32 v104, v228
	v_mov_b32_e32 v105, v229
	v_add_u32_e32 v90, 0x90, v146
	v_ashrrev_i32_e32 v91, 31, v90
	v_lshlrev_b64 v[72:73], 11, v[90:91]
	v_add_u32_e32 v80, 0xa0, v146
	v_lshl_add_u64 v[72:73], v[148:149], 0, v[72:73]
	v_ashrrev_i32_e32 v81, 31, v80
	v_mov_b32_e32 v100, v230
	v_mov_b32_e32 v101, v231
	v_mov_b32_e32 v98, v232
	v_mov_b32_e32 v99, v233
	v_mov_b32_e32 v96, v234
	v_mov_b32_e32 v97, v235
	v_mov_b32_e32 v94, v236
	v_mov_b32_e32 v95, v237
	v_lshlrev_b64 v[72:73], 11, v[80:81]
	v_lshl_add_u64 v[72:73], v[148:149], 0, v[72:73]
	v_mov_b32_e32 v92, v238
	v_mov_b32_e32 v93, v239
	v_mov_b32_e32 v88, v240
	v_mov_b32_e32 v89, v241
	v_mov_b32_e32 v86, v242
	v_mov_b32_e32 v87, v243
	v_mov_b32_e32 v84, v244
	v_mov_b32_e32 v85, v245
	v_add_u32_e32 v72, 0xb0, v146
	v_ashrrev_i32_e32 v73, 31, v72
	v_lshlrev_b64 v[74:75], 11, v[72:73]
	v_lshl_add_u64 v[74:75], v[148:149], 0, v[74:75]
	global_load_dwordx2 v[82:83], v[74:75], off
	global_load_dwordx2 v[78:79], v[74:75], off offset:32
	global_load_dwordx2 v[76:77], v[74:75], off offset:256
	s_nop 0
	global_load_dwordx2 v[74:75], v[74:75], off offset:288
	v_mov_b32_e32 v137, v136
	v_lshlrev_b32_e32 v114, 16, v112
	v_and_b32_e32 v115, 0xffff0000, v112
	v_lshlrev_b32_e32 v112, 16, v113
	v_and_b32_e32 v113, 0xffff0000, v113
	v_pk_fma_f32 v[68:69], v[138:139], v[68:69], v[114:115]
	v_pk_fma_f32 v[70:71], v[136:137], v[70:71], v[112:113]
	v_cvt_pk_bf16_f32 v112, v68, v69
	v_cvt_pk_bf16_f32 v113, v70, v71
	v_and_b32_e32 v71, 0xffff0000, v112
	v_lshl_add_u64 v[68:69], s[26:27], 0, v[110:111]
	v_lshlrev_b32_e32 v70, 16, v112
	v_and_b32_e32 v111, 0xffff0000, v113
	v_mul_f32_e32 v71, v71, v71
	v_lshlrev_b32_e32 v110, 16, v113
	v_fmac_f32_e32 v71, v70, v70
	v_mul_f32_e32 v70, v111, v111
	v_fmac_f32_e32 v70, v110, v110
	v_add_f32_e32 v110, v71, v70
	v_lshlrev_b32_e32 v70, 16, v108
	v_and_b32_e32 v71, 0xffff0000, v108
	v_lshlrev_b32_e32 v108, 16, v109
	v_and_b32_e32 v109, 0xffff0000, v109
	v_pk_fma_f32 v[66:67], v[136:137], v[66:67], v[108:109]
	v_pk_fma_f32 v[64:65], v[138:139], v[64:65], v[70:71]
	v_lshl_add_u64 v[68:69], v[144:145], 1, v[68:69]
	v_cvt_pk_bf16_f32 v64, v64, v65
	v_cvt_pk_bf16_f32 v65, v66, v67
	global_store_dwordx2 v[68:69], v[64:65], off offset:32
	v_lshlrev_b32_e32 v66, 16, v64
	v_and_b32_e32 v64, 0xffff0000, v64
	v_lshlrev_b32_e32 v67, 16, v65
	v_and_b32_e32 v65, 0xffff0000, v65
	v_mul_f32_e32 v64, v64, v64
	v_mul_f32_e32 v65, v65, v65
	v_fmac_f32_e32 v64, v66, v66
	v_fmac_f32_e32 v65, v67, v67
	v_add_f32_e32 v64, v64, v65
	v_add_f32_e32 v70, v110, v64
	v_lshlrev_b32_e32 v64, 16, v106
	v_and_b32_e32 v65, 0xffff0000, v106
	v_lshlrev_b32_e32 v66, 16, v107
	v_and_b32_e32 v67, 0xffff0000, v107
	v_pk_fma_f32 v[62:63], v[136:137], v[62:63], v[66:67]
	v_pk_fma_f32 v[60:61], v[138:139], v[60:61], v[64:65]
	global_store_dwordx2 v[68:69], v[112:113], off
	v_cvt_pk_bf16_f32 v60, v60, v61
	v_cvt_pk_bf16_f32 v61, v62, v63
	global_store_dwordx2 v[68:69], v[60:61], off offset:256
	v_lshlrev_b32_e32 v62, 16, v60
	v_and_b32_e32 v60, 0xffff0000, v60
	v_lshlrev_b32_e32 v63, 16, v61
	v_and_b32_e32 v61, 0xffff0000, v61
	v_mul_f32_e32 v60, v60, v60
	v_mul_f32_e32 v61, v61, v61
	v_fmac_f32_e32 v60, v62, v62
	v_fmac_f32_e32 v61, v63, v63
	v_add_f32_e32 v60, v60, v61
	v_add_f32_e32 v64, v70, v60
	v_lshlrev_b32_e32 v60, 16, v104
	v_and_b32_e32 v61, 0xffff0000, v104
	v_lshlrev_b32_e32 v62, 16, v105
	v_and_b32_e32 v63, 0xffff0000, v105
	v_pk_fma_f32 v[58:59], v[136:137], v[58:59], v[62:63]
	v_pk_fma_f32 v[56:57], v[138:139], v[56:57], v[60:61]
	s_nop 0
	v_cvt_pk_bf16_f32 v56, v56, v57
	v_cvt_pk_bf16_f32 v57, v58, v59
	global_store_dwordx2 v[68:69], v[56:57], off offset:288
	v_lshlrev_b32_e32 v58, 16, v56
	v_and_b32_e32 v56, 0xffff0000, v56
	v_lshlrev_b32_e32 v59, 16, v57
	v_and_b32_e32 v57, 0xffff0000, v57
	v_mul_f32_e32 v56, v56, v56
	v_mul_f32_e32 v57, v57, v57
	v_fmac_f32_e32 v56, v58, v58
	v_fmac_f32_e32 v57, v59, v59
	v_add_f32_e32 v56, v56, v57
	v_add_f32_e32 v56, v64, v56
	ds_bpermute_b32 v57, v212, v56
	s_waitcnt lgkmcnt(0)
	v_add_f32_e32 v56, v56, v57
	ds_bpermute_b32 v57, v211, v56
	s_and_saveexec_b64 s[14:15], s[42:43]
	s_cbranch_execz .LBB0_234
	v_readlane_b32 s16, v252, 28
	v_lshlrev_b64 v[58:59], 6, v[102:103]
	v_readlane_b32 s17, v252, 29
	s_lshl_b32 s36, s58, 2
	s_waitcnt lgkmcnt(0)
	v_add_f32_e32 v56, v56, v57
	v_lshl_add_u64 v[58:59], s[16:17], 0, v[58:59]
	v_lshl_add_u64 v[58:59], s[24:25], 2, v[58:59]
	v_lshl_add_u64 v[58:59], v[58:59], 0, s[36:37]
	global_store_dword v[58:59], v56, off
; __device__ __forceinline__ unsigned cvt_pk_bf16(float lo, float hi) { bf16v2_t r = __builtin_convertvector((f32x2_t){lo, hi}, bf16v2_t); return __builtin_bit_cast(unsigned, r); }
;     static __device__ __forceinline__ f32x4 unpack4(u32x2_ t) { return (f32x4){__uint_as_float(t.x << 16), __uint_as_float(t.x & 0xffff0000u), __uint_as_float(t.y << 16), __uint_as_float(t.y & 0xffff0000u)}; }
;     __device__ __forceinline__ void operator()(const f32x4 (&acc)[2][2][4][2], const Unit& u, int wr, int wc, int fr, int fq) const {
;     ...
;                 for (int m = 0; m < 4; ++m) {
;                     const int row = row0 + ai * HALF + m * 16; const size_t off = (size_t)row * ldc + col0; float ss = 0.f;
; #pragma unroll
;                     for (int bj = 0; bj < 2; ++bj)
; #pragma unroll
;                         for (int n = 0; n < 2; ++n) { const size_t o = off + bj * HALF + n * 16;
;                             f32x4 v = unpack4(bb[m][bj][n]) + acc[ai][bj][m][n] * scale;
;                             u32x2_ w; w.x = cvt_pk_bf16(v[0], v[1]); w.y = cvt_pk_bf16(v[2], v[3]); *(u32x2_*)(xb + o) = w;
;                             if (out32) *(f32x4*)(out32 + o) = v; else v = unpack4(w);
;                             ss += (v[0] * v[0] + v[1] * v[1]) + (v[2] * v[2] + v[3] * v[3]); }
;                     ss += __shfl_xor(ss, 16); ss += __shfl_xor(ss, 32);
;                     if (fq == 0) ssq[(size_t)row * 16 + 4 * u.pn + wc] = ss;
.LBB0_234:
	s_or_b64 exec, exec, s[14:15]
	v_lshlrev_b32_e32 v56, 16, v100
	s_waitcnt lgkmcnt(0)
	v_and_b32_e32 v57, 0xffff0000, v100
	v_lshlrev_b32_e32 v58, 16, v101
	v_and_b32_e32 v59, 0xffff0000, v101
	v_pk_fma_f32 v[52:53], v[138:139], v[52:53], v[56:57]
	v_pk_fma_f32 v[54:55], v[136:137], v[54:55], v[58:59]
	v_cvt_pk_bf16_f32 v52, v52, v53
	v_cvt_pk_bf16_f32 v53, v54, v55
	v_and_b32_e32 v55, 0xffff0000, v52
	v_lshlrev_b32_e32 v54, 16, v52
	v_and_b32_e32 v57, 0xffff0000, v53
	v_mul_f32_e32 v55, v55, v55
	v_lshlrev_b32_e32 v56, 16, v53
	v_fmac_f32_e32 v55, v54, v54
	v_mul_f32_e32 v54, v57, v57
	v_fmac_f32_e32 v54, v56, v56
	v_add_f32_e32 v58, v55, v54
	v_lshlrev_b32_e32 v54, 16, v98
	v_and_b32_e32 v55, 0xffff0000, v98
	v_lshlrev_b32_e32 v56, 16, v99
	v_and_b32_e32 v57, 0xffff0000, v99
	v_pk_fma_f32 v[48:49], v[138:139], v[48:49], v[54:55]
	v_pk_fma_f32 v[50:51], v[136:137], v[50:51], v[56:57]
	v_cvt_pk_bf16_f32 v48, v48, v49
	v_cvt_pk_bf16_f32 v49, v50, v51
	v_and_b32_e32 v51, 0xffff0000, v48
	v_lshlrev_b32_e32 v50, 16, v48
	v_and_b32_e32 v55, 0xffff0000, v49
	v_mul_f32_e32 v51, v51, v51
	v_lshlrev_b32_e32 v54, 16, v49
	v_fmac_f32_e32 v51, v50, v50
	v_mul_f32_e32 v50, v55, v55
	v_fmac_f32_e32 v50, v54, v54
	v_add_f32_e32 v50, v51, v50
	v_add_f32_e32 v56, v58, v50
	v_lshlrev_b32_e32 v50, 16, v96
	v_and_b32_e32 v51, 0xffff0000, v96
	v_lshlrev_b32_e32 v54, 16, v97
	v_and_b32_e32 v55, 0xffff0000, v97
	v_pk_fma_f32 v[44:45], v[138:139], v[44:45], v[50:51]
	v_pk_fma_f32 v[46:47], v[136:137], v[46:47], v[54:55]
	v_cvt_pk_bf16_f32 v44, v44, v45
	v_cvt_pk_bf16_f32 v45, v46, v47
	v_and_b32_e32 v47, 0xffff0000, v44
	v_lshlrev_b32_e32 v46, 16, v44
	v_and_b32_e32 v51, 0xffff0000, v45
	v_mul_f32_e32 v47, v47, v47
	v_lshlrev_b32_e32 v50, 16, v45
	v_fmac_f32_e32 v47, v46, v46
	v_mul_f32_e32 v46, v51, v51
	v_fmac_f32_e32 v46, v50, v50
	v_add_f32_e32 v46, v47, v46
	v_add_f32_e32 v54, v56, v46
	v_lshlrev_b32_e32 v46, 16, v94
	v_and_b32_e32 v47, 0xffff0000, v94
	v_lshlrev_b32_e32 v50, 16, v95
	v_and_b32_e32 v51, 0xffff0000, v95
	v_pk_fma_f32 v[40:41], v[138:139], v[40:41], v[46:47]
	v_pk_fma_f32 v[42:43], v[136:137], v[42:43], v[50:51]
	v_cvt_pk_bf16_f32 v46, v40, v41
	v_cvt_pk_bf16_f32 v47, v42, v43
	v_and_b32_e32 v41, 0xffff0000, v46
	v_lshlrev_b32_e32 v40, 16, v46
	v_and_b32_e32 v43, 0xffff0000, v47
	v_mul_f32_e32 v41, v41, v41
	v_lshlrev_b32_e32 v42, 16, v47
	v_fmac_f32_e32 v41, v40, v40
	v_mul_f32_e32 v40, v43, v43
	v_fmac_f32_e32 v40, v42, v42
	v_add_f32_e32 v40, v41, v40
	v_add_f32_e32 v50, v54, v40
	ds_bpermute_b32 v51, v212, v50
	v_lshlrev_b64 v[40:41], 10, v[90:91]
	v_lshl_add_u64 v[40:41], v[40:41], 1, s[26:27]
	v_lshl_add_u64 v[42:43], v[144:145], 1, v[40:41]
	global_store_dwordx2 v[42:43], v[52:53], off
	global_store_dwordx2 v[42:43], v[48:49], off offset:32
	global_store_dwordx2 v[42:43], v[44:45], off offset:256
	global_store_dwordx2 v[42:43], v[46:47], off offset:288
	s_waitcnt lgkmcnt(0)
	v_add_f32_e32 v40, v50, v51
	ds_bpermute_b32 v41, v211, v40
	s_and_saveexec_b64 s[14:15], s[42:43]
	s_cbranch_execz .LBB0_236
	v_readlane_b32 s16, v252, 28
	v_lshlrev_b64 v[42:43], 6, v[90:91]
	v_readlane_b32 s17, v252, 29
	s_lshl_b32 s36, s58, 2
	s_waitcnt lgkmcnt(0)
	v_add_f32_e32 v40, v40, v41
	v_lshl_add_u64 v[42:43], s[16:17], 0, v[42:43]
	v_lshl_add_u64 v[42:43], s[24:25], 2, v[42:43]
	v_lshl_add_u64 v[42:43], v[42:43], 0, s[36:37]
	global_store_dword v[42:43], v40, off
.LBB0_236:
	s_or_b64 exec, exec, s[14:15]
	v_lshlrev_b32_e32 v40, 16, v92
	s_waitcnt lgkmcnt(0)
	v_and_b32_e32 v41, 0xffff0000, v92
	v_lshlrev_b32_e32 v42, 16, v93
	v_and_b32_e32 v43, 0xffff0000, v93
	v_mov_b32_e32 v137, v136
	v_pk_fma_f32 v[36:37], v[138:139], v[36:37], v[40:41]
	v_pk_fma_f32 v[38:39], v[136:137], v[38:39], v[42:43]
	v_cvt_pk_bf16_f32 v36, v36, v37
	v_cvt_pk_bf16_f32 v37, v38, v39
	v_and_b32_e32 v39, 0xffff0000, v36
	v_lshlrev_b32_e32 v38, 16, v36
	v_and_b32_e32 v41, 0xffff0000, v37
	v_mul_f32_e32 v39, v39, v39
	v_lshlrev_b32_e32 v40, 16, v37
	v_fmac_f32_e32 v39, v38, v38
	v_mul_f32_e32 v38, v41, v41
	v_fmac_f32_e32 v38, v40, v40
	v_add_f32_e32 v42, v39, v38
	v_lshlrev_b32_e32 v38, 16, v88
	v_and_b32_e32 v39, 0xffff0000, v88
	v_lshlrev_b32_e32 v40, 16, v89
	v_and_b32_e32 v41, 0xffff0000, v89
	v_pk_fma_f32 v[32:33], v[138:139], v[32:33], v[38:39]
	v_pk_fma_f32 v[34:35], v[136:137], v[34:35], v[40:41]
	v_cvt_pk_bf16_f32 v32, v32, v33
	v_cvt_pk_bf16_f32 v33, v34, v35
	v_and_b32_e32 v35, 0xffff0000, v32
	v_lshlrev_b32_e32 v34, 16, v32
	v_and_b32_e32 v39, 0xffff0000, v33
	v_mul_f32_e32 v35, v35, v35
	v_lshlrev_b32_e32 v38, 16, v33
	v_fmac_f32_e32 v35, v34, v34
	v_mul_f32_e32 v34, v39, v39
	v_fmac_f32_e32 v34, v38, v38
	v_add_f32_e32 v34, v35, v34
	v_add_f32_e32 v40, v42, v34
	v_lshlrev_b32_e32 v34, 16, v86
	v_and_b32_e32 v35, 0xffff0000, v86
	v_lshlrev_b32_e32 v38, 16, v87
	v_and_b32_e32 v39, 0xffff0000, v87
	v_pk_fma_f32 v[28:29], v[138:139], v[28:29], v[34:35]
	v_pk_fma_f32 v[30:31], v[136:137], v[30:31], v[38:39]
	v_cvt_pk_bf16_f32 v28, v28, v29
	v_cvt_pk_bf16_f32 v29, v30, v31
	v_and_b32_e32 v31, 0xffff0000, v28
	v_lshlrev_b32_e32 v30, 16, v28
	v_and_b32_e32 v35, 0xffff0000, v29
	v_mul_f32_e32 v31, v31, v31
	v_lshlrev_b32_e32 v34, 16, v29
	v_fmac_f32_e32 v31, v30, v30
	v_mul_f32_e32 v30, v35, v35
	v_fmac_f32_e32 v30, v34, v34
	v_add_f32_e32 v30, v31, v30
	v_add_f32_e32 v38, v40, v30
	v_lshlrev_b32_e32 v30, 16, v84
	v_and_b32_e32 v31, 0xffff0000, v84
	v_lshlrev_b32_e32 v34, 16, v85
	v_and_b32_e32 v35, 0xffff0000, v85
	v_pk_fma_f32 v[24:25], v[138:139], v[24:25], v[30:31]
	v_pk_fma_f32 v[26:27], v[136:137], v[26:27], v[34:35]
	v_cvt_pk_bf16_f32 v30, v24, v25
	v_cvt_pk_bf16_f32 v31, v26, v27
	v_and_b32_e32 v25, 0xffff0000, v30
	v_lshlrev_b32_e32 v24, 16, v30
	v_and_b32_e32 v27, 0xffff0000, v31
	v_mul_f32_e32 v25, v25, v25
	v_lshlrev_b32_e32 v26, 16, v31
	v_fmac_f32_e32 v25, v24, v24
	v_mul_f32_e32 v24, v27, v27
	v_fmac_f32_e32 v24, v26, v26
	v_add_f32_e32 v24, v25, v24
	v_add_f32_e32 v34, v38, v24
	ds_bpermute_b32 v35, v212, v34
	v_lshlrev_b64 v[24:25], 10, v[80:81]
	v_lshl_add_u64 v[24:25], v[24:25], 1, s[26:27]
	v_lshl_add_u64 v[26:27], v[144:145], 1, v[24:25]
	global_store_dwordx2 v[26:27], v[36:37], off
	global_store_dwordx2 v[26:27], v[32:33], off offset:32
	global_store_dwordx2 v[26:27], v[28:29], off offset:256
	global_store_dwordx2 v[26:27], v[30:31], off offset:288
	s_waitcnt lgkmcnt(0)
	v_add_f32_e32 v24, v34, v35
	ds_bpermute_b32 v25, v211, v24
	s_and_saveexec_b64 s[14:15], s[42:43]
	s_cbranch_execz .LBB0_238
	v_readlane_b32 s16, v252, 28
	v_lshlrev_b64 v[26:27], 6, v[80:81]
	v_readlane_b32 s17, v252, 29
	s_lshl_b32 s36, s58, 2
	s_waitcnt lgkmcnt(0)
	v_add_f32_e32 v24, v24, v25
	v_lshl_add_u64 v[26:27], s[16:17], 0, v[26:27]
	v_lshl_add_u64 v[26:27], s[24:25], 2, v[26:27]
	v_lshl_add_u64 v[26:27], v[26:27], 0, s[36:37]
	global_store_dword v[26:27], v24, off
